# P9 (FFN2-in) tile-epilogue fp8 stores plain instead of sc1, on top of v129
# speedup vs baseline: 1.0006x; 1.0006x over previous
.LBB0_622:
	v_pk_mul_f32 v[144:145], v[122:123], s[14:15] op_sel_hi:[1,0]
	v_pk_mul_f32 v[122:123], v[122:123], v[126:127]
	v_pk_mul_f32 v[126:127], v[114:115], s[14:15] op_sel_hi:[1,0]
	v_pk_mul_f32 v[146:147], v[124:125], s[14:15] op_sel_hi:[1,0]
	v_exp_f32_e32 v126, v126
	v_exp_f32_e32 v127, v127
	v_pk_mul_f32 v[124:125], v[124:125], v[128:129]
	v_pk_mul_f32 v[128:129], v[116:117], s[14:15] op_sel_hi:[1,0]
	v_pk_mul_f32 v[114:115], v[114:115], v[118:119]
	v_exp_f32_e32 v128, v128
	v_exp_f32_e32 v129, v129
	v_pk_add_f32 v[126:127], v[126:127], 1.0 op_sel_hi:[1,0]
	v_pk_mul_f32 v[116:117], v[116:117], v[120:121]
	v_rcp_f32_e32 v126, v126
	v_rcp_f32_e32 v127, v127
	v_pk_add_f32 v[128:129], v[128:129], 1.0 op_sel_hi:[1,0]
	v_pk_mul_f32 v[120:121], v[106:107], s[14:15] op_sel_hi:[1,0]
	v_rcp_f32_e32 v128, v128
	v_rcp_f32_e32 v129, v129
	v_pk_mul_f32 v[118:119], v[126:127], v[114:115]
	v_mov_b32_e32 v115, 0
	v_cvt_pk_fp8_f32 v115, v118, v119
	v_pk_mul_f32 v[106:107], v[106:107], v[110:111]
	v_pk_mul_f32 v[110:111], v[98:99], s[14:15] op_sel_hi:[1,0]
	v_pk_mul_f32 v[116:117], v[128:129], v[116:117]
	v_exp_f32_e32 v110, v110
	v_exp_f32_e32 v111, v111
	v_cvt_pk_fp8_f32 v115, v116, v117 op_sel:[0,0,1]
	v_pk_mul_f32 v[116:117], v[100:101], s[14:15] op_sel_hi:[1,0]
	v_pk_mul_f32 v[98:99], v[98:99], v[102:103]
	v_pk_add_f32 v[110:111], v[110:111], 1.0 op_sel_hi:[1,0]
	v_exp_f32_e32 v116, v116
	v_exp_f32_e32 v117, v117
	v_rcp_f32_e32 v110, v110
	v_rcp_f32_e32 v111, v111
	v_lshl_add_u32 v148, s30, 8, v139
	v_pk_add_f32 v[102:103], v[116:117], 1.0 op_sel_hi:[1,0]
	v_mov_b32_e32 v117, 0
	v_pk_mul_f32 v[98:99], v[110:111], v[98:99]
	v_rcp_f32_e32 v102, v102
	v_rcp_f32_e32 v103, v103
	v_cvt_pk_fp8_f32 v117, v98, v99
	v_pk_mul_f32 v[98:99], v[100:101], v[104:105]
	s_lshl_b32 s8, s75, 7
	v_pk_mul_f32 v[98:99], v[102:103], v[98:99]
	v_pk_mul_f32 v[100:101], v[92:93], s[14:15] op_sel_hi:[1,0]
	v_cvt_pk_fp8_f32 v117, v98, v99 op_sel:[0,0,1]
	v_mul_lo_u32 v98, v148, s74
	v_add3_u32 v102, v140, s8, v98
	v_pk_mul_f32 v[98:99], v[90:91], s[14:15] op_sel_hi:[1,0]
	v_pk_mul_f32 v[90:91], v[90:91], v[94:95]
	v_pk_mul_f32 v[94:95], v[82:83], s[14:15] op_sel_hi:[1,0]
	v_pk_mul_f32 v[92:93], v[92:93], v[96:97]
	v_exp_f32_e32 v94, v94
	v_exp_f32_e32 v95, v95
	v_pk_mul_f32 v[96:97], v[84:85], s[14:15] op_sel_hi:[1,0]
	v_pk_mul_f32 v[82:83], v[82:83], v[86:87]
	v_exp_f32_e32 v96, v96
	v_exp_f32_e32 v97, v97
	v_pk_add_f32 v[94:95], v[94:95], 1.0 op_sel_hi:[1,0]
	v_pk_mul_f32 v[84:85], v[84:85], v[88:89]
	v_rcp_f32_e32 v94, v94
	v_rcp_f32_e32 v95, v95
	v_pk_add_f32 v[96:97], v[96:97], 1.0 op_sel_hi:[1,0]
	v_pk_mul_f32 v[88:89], v[74:75], s[14:15] op_sel_hi:[1,0]
	v_rcp_f32_e32 v96, v96
	v_rcp_f32_e32 v97, v97
	v_pk_mul_f32 v[86:87], v[94:95], v[82:83]
	v_mov_b32_e32 v83, 0
	v_cvt_pk_fp8_f32 v83, v86, v87
	v_pk_mul_f32 v[74:75], v[74:75], v[78:79]
	v_pk_mul_f32 v[78:79], v[54:55], s[14:15] op_sel_hi:[1,0]
	v_exp_f32_e32 v144, v144
	v_exp_f32_e32 v145, v145
	v_exp_f32_e32 v120, v120
	v_exp_f32_e32 v121, v121
	v_exp_f32_e32 v98, v98
	v_exp_f32_e32 v99, v99
	v_exp_f32_e32 v88, v88
	v_exp_f32_e32 v89, v89
	v_exp_f32_e32 v78, v78
	v_exp_f32_e32 v79, v79
	v_pk_mul_f32 v[84:85], v[96:97], v[84:85]
	v_pk_mul_f32 v[112:113], v[108:109], v[112:113]
	v_pk_mul_f32 v[108:109], v[108:109], s[14:15] op_sel_hi:[1,0]
	v_cvt_pk_fp8_f32 v83, v84, v85 op_sel:[0,0,1]
	v_pk_mul_f32 v[80:81], v[76:77], v[80:81]
	v_pk_mul_f32 v[76:77], v[76:77], s[14:15] op_sel_hi:[1,0]
	v_pk_mul_f32 v[84:85], v[56:57], s[14:15] op_sel_hi:[1,0]
	v_exp_f32_e32 v146, v146
	v_exp_f32_e32 v147, v147
	v_pk_add_f32 v[144:145], v[144:145], 1.0 op_sel_hi:[1,0]
	v_pk_add_f32 v[118:119], v[120:121], 1.0 op_sel_hi:[1,0]
	v_exp_f32_e32 v108, v108
	v_exp_f32_e32 v109, v109
	v_exp_f32_e32 v100, v100
	v_exp_f32_e32 v101, v101
	v_pk_add_f32 v[98:99], v[98:99], 1.0 op_sel_hi:[1,0]
	v_pk_add_f32 v[86:87], v[88:89], 1.0 op_sel_hi:[1,0]
	v_exp_f32_e32 v76, v76
	v_exp_f32_e32 v77, v77
	v_pk_add_f32 v[78:79], v[78:79], 1.0 op_sel_hi:[1,0]
	v_exp_f32_e32 v84, v84
	v_exp_f32_e32 v85, v85
	v_rcp_f32_e32 v144, v144
	v_rcp_f32_e32 v145, v145
	v_rcp_f32_e32 v118, v118
	v_rcp_f32_e32 v119, v119
	v_rcp_f32_e32 v98, v98
	v_rcp_f32_e32 v99, v99
	v_rcp_f32_e32 v86, v86
	v_rcp_f32_e32 v87, v87
	v_rcp_f32_e32 v78, v78
	v_rcp_f32_e32 v79, v79
	v_pk_add_f32 v[146:147], v[146:147], 1.0 op_sel_hi:[1,0]
	v_pk_add_f32 v[108:109], v[108:109], 1.0 op_sel_hi:[1,0]
	v_pk_add_f32 v[100:101], v[100:101], 1.0 op_sel_hi:[1,0]
	v_pk_add_f32 v[76:77], v[76:77], 1.0 op_sel_hi:[1,0]
	v_pk_mul_f32 v[54:55], v[54:55], v[62:63]
	v_pk_add_f32 v[62:63], v[84:85], 1.0 op_sel_hi:[1,0]
	v_rcp_f32_e32 v146, v146
	v_rcp_f32_e32 v147, v147
	v_pk_mul_f32 v[122:123], v[144:145], v[122:123]
	v_mov_b32_e32 v114, 0
	v_pk_mul_f32 v[106:107], v[118:119], v[106:107]
	v_rcp_f32_e32 v108, v108
	v_rcp_f32_e32 v109, v109
	v_mov_b32_e32 v116, 0
	v_rcp_f32_e32 v100, v100
	v_rcp_f32_e32 v101, v101
	v_pk_mul_f32 v[90:91], v[98:99], v[90:91]
	v_mov_b32_e32 v82, 0
	v_pk_mul_f32 v[74:75], v[86:87], v[74:75]
	v_rcp_f32_e32 v76, v76
	v_rcp_f32_e32 v77, v77
	v_pk_mul_f32 v[54:55], v[78:79], v[54:55]
	v_rcp_f32_e32 v62, v62
	v_rcp_f32_e32 v63, v63
	v_mov_b32_e32 v84, 0
	v_mov_b32_e32 v85, 0
	v_cvt_pk_fp8_f32 v114, v122, v123
	v_cvt_pk_fp8_f32 v116, v106, v107
	v_cvt_pk_fp8_f32 v82, v90, v91
	v_cvt_pk_fp8_f32 v84, v74, v75
	v_cvt_pk_fp8_f32 v85, v54, v55
	v_pk_mul_f32 v[54:55], v[56:57], v[64:65]
	v_pk_mul_f32 v[124:125], v[146:147], v[124:125]
	v_pk_mul_f32 v[108:109], v[108:109], v[112:113]
	v_pk_mul_f32 v[92:93], v[100:101], v[92:93]
	v_pk_mul_f32 v[76:77], v[76:77], v[80:81]
	v_pk_mul_f32 v[54:55], v[62:63], v[54:55]
	v_cvt_pk_fp8_f32 v114, v124, v125 op_sel:[0,0,1]
	v_cvt_pk_fp8_f32 v116, v108, v109 op_sel:[0,0,1]
	v_cvt_pk_fp8_f32 v82, v92, v93 op_sel:[0,0,1]
	v_cvt_pk_fp8_f32 v84, v76, v77 op_sel:[0,0,1]
	v_cvt_pk_fp8_f32 v85, v54, v55 op_sel:[0,0,1]
	v_pk_mul_f32 v[56:57], v[68:69], s[14:15] op_sel_hi:[1,0]
	v_permlane16_swap_b32_e32 v114, v116
	v_exp_f32_e32 v56, v56
	v_exp_f32_e32 v57, v57
	v_permlane16_swap_b32_e32 v115, v117
	v_permlane16_swap_b32_e32 v82, v84
	v_permlane16_swap_b32_e32 v83, v85
	v_add_u32_e32 v54, 0x16000, v102
	buffer_store_dwordx4 v[114:117], v102, s[4:7], 0 offen
	buffer_store_dwordx4 v[82:85], v54, s[4:7], 0 offen
	v_pk_mul_f32 v[54:55], v[66:67], s[14:15] op_sel_hi:[1,0]
	v_pk_add_f32 v[56:57], v[56:57], 1.0 op_sel_hi:[1,0]
	v_exp_f32_e32 v54, v54
	v_exp_f32_e32 v55, v55
	v_rcp_f32_e32 v56, v56
	v_rcp_f32_e32 v57, v57
	v_pk_mul_f32 v[62:63], v[68:69], v[72:73]
	v_pk_add_f32 v[54:55], v[54:55], 1.0 op_sel_hi:[1,0]
	v_pk_mul_f32 v[64:65], v[66:67], v[70:71]
	v_rcp_f32_e32 v54, v54
	v_rcp_f32_e32 v55, v55
	v_pk_mul_f32 v[56:57], v[56:57], v[62:63]
	v_pk_mul_f32 v[62:63], v[50:51], s[14:15] op_sel_hi:[1,0]
	v_pk_mul_f32 v[50:51], v[50:51], v[58:59]
	v_exp_f32_e32 v62, v62
	v_exp_f32_e32 v63, v63
	v_pk_mul_f32 v[54:55], v[54:55], v[64:65]
	v_pk_mul_f32 v[64:65], v[52:53], s[14:15] op_sel_hi:[1,0]
	v_pk_mul_f32 v[52:53], v[52:53], v[60:61]
	v_exp_f32_e32 v64, v64
	v_exp_f32_e32 v65, v65
	v_pk_add_f32 v[62:63], v[62:63], 1.0 op_sel_hi:[1,0]
	v_pk_mul_f32 v[48:49], v[44:45], v[48:49]
	v_rcp_f32_e32 v62, v62
	v_rcp_f32_e32 v63, v63
	v_pk_add_f32 v[64:65], v[64:65], 1.0 op_sel_hi:[1,0]
	v_pk_mul_f32 v[44:45], v[44:45], s[14:15] op_sel_hi:[1,0]
	v_rcp_f32_e32 v64, v64
	v_rcp_f32_e32 v65, v65
	v_pk_mul_f32 v[58:59], v[62:63], v[50:51]
	v_mov_b32_e32 v50, 0
	v_mov_b32_e32 v51, 0
	v_cvt_pk_fp8_f32 v50, v54, v55
	v_pk_mul_f32 v[54:55], v[42:43], s[14:15] op_sel_hi:[1,0]
	v_cvt_pk_fp8_f32 v51, v58, v59
	v_pk_mul_f32 v[42:43], v[42:43], v[46:47]
	v_pk_mul_f32 v[46:47], v[34:35], s[14:15] op_sel_hi:[1,0]
	v_exp_f32_e32 v54, v54
	v_exp_f32_e32 v55, v55
	v_exp_f32_e32 v46, v46
	v_exp_f32_e32 v47, v47
	v_pk_mul_f32 v[52:53], v[64:65], v[52:53]
	v_pk_add_f32 v[54:55], v[54:55], 1.0 op_sel_hi:[1,0]
	v_cvt_pk_fp8_f32 v51, v52, v53 op_sel:[0,0,1]
	v_pk_mul_f32 v[52:53], v[36:37], s[14:15] op_sel_hi:[1,0]
	v_exp_f32_e32 v44, v44
	v_exp_f32_e32 v45, v45
	v_pk_add_f32 v[46:47], v[46:47], 1.0 op_sel_hi:[1,0]
	v_exp_f32_e32 v52, v52
	v_exp_f32_e32 v53, v53
	v_rcp_f32_e32 v54, v54
	v_rcp_f32_e32 v55, v55
	v_rcp_f32_e32 v46, v46
	v_rcp_f32_e32 v47, v47
	v_pk_add_f32 v[44:45], v[44:45], 1.0 op_sel_hi:[1,0]
	v_pk_mul_f32 v[34:35], v[34:35], v[38:39]
	v_pk_add_f32 v[38:39], v[52:53], 1.0 op_sel_hi:[1,0]
	v_pk_mul_f32 v[42:43], v[54:55], v[42:43]
	v_rcp_f32_e32 v44, v44
	v_rcp_f32_e32 v45, v45
	v_pk_mul_f32 v[34:35], v[46:47], v[34:35]
	v_rcp_f32_e32 v38, v38
	v_rcp_f32_e32 v39, v39
	v_mov_b32_e32 v52, 0
	v_mov_b32_e32 v53, 0
	v_cvt_pk_fp8_f32 v52, v42, v43
	v_cvt_pk_fp8_f32 v53, v34, v35
	v_pk_mul_f32 v[34:35], v[36:37], v[40:41]
	v_pk_mul_f32 v[44:45], v[44:45], v[48:49]
	v_pk_mul_f32 v[34:35], v[38:39], v[34:35]
	v_cvt_pk_fp8_f32 v50, v56, v57 op_sel:[0,0,1]
	v_cvt_pk_fp8_f32 v52, v44, v45 op_sel:[0,0,1]
	v_cvt_pk_fp8_f32 v53, v34, v35 op_sel:[0,0,1]
	v_add_u32_e32 v34, 0x58000, v102
	v_pk_mul_f32 v[36:37], v[28:29], s[14:15] op_sel_hi:[1,0]
	v_permlane16_swap_b32_e32 v50, v52
	v_permlane16_swap_b32_e32 v51, v53
	buffer_store_dwordx4 v[50:53], v34, s[4:7], 0 offen
	v_pk_mul_f32 v[34:35], v[26:27], s[14:15] op_sel_hi:[1,0]
	v_pk_mul_f32 v[26:27], v[26:27], v[30:31]
	v_pk_mul_f32 v[30:31], v[18:19], s[14:15] op_sel_hi:[1,0]
	v_pk_mul_f32 v[28:29], v[28:29], v[32:33]
	v_exp_f32_e32 v30, v30
	v_exp_f32_e32 v31, v31
	v_pk_mul_f32 v[32:33], v[20:21], s[14:15] op_sel_hi:[1,0]
	v_pk_mul_f32 v[18:19], v[18:19], v[22:23]
	v_exp_f32_e32 v32, v32
	v_exp_f32_e32 v33, v33
	v_pk_add_f32 v[30:31], v[30:31], 1.0 op_sel_hi:[1,0]
	v_pk_mul_f32 v[20:21], v[20:21], v[24:25]
	v_rcp_f32_e32 v30, v30
	v_rcp_f32_e32 v31, v31
	v_pk_add_f32 v[32:33], v[32:33], 1.0 op_sel_hi:[1,0]
	v_pk_mul_f32 v[24:25], v[10:11], s[14:15] op_sel_hi:[1,0]
	v_rcp_f32_e32 v32, v32
	v_rcp_f32_e32 v33, v33
	v_pk_mul_f32 v[22:23], v[30:31], v[18:19]
	v_mov_b32_e32 v19, 0
	v_cvt_pk_fp8_f32 v19, v22, v23
	v_pk_mul_f32 v[10:11], v[10:11], v[14:15]
	v_pk_mul_f32 v[14:15], v[2:3], s[14:15] op_sel_hi:[1,0]
	v_exp_f32_e32 v34, v34
	v_exp_f32_e32 v35, v35
	v_exp_f32_e32 v24, v24
	v_exp_f32_e32 v25, v25
	v_exp_f32_e32 v14, v14
	v_exp_f32_e32 v15, v15
	v_pk_mul_f32 v[20:21], v[32:33], v[20:21]
	v_pk_mul_f32 v[16:17], v[12:13], v[16:17]
	v_cvt_pk_fp8_f32 v19, v20, v21 op_sel:[0,0,1]
	v_pk_mul_f32 v[12:13], v[12:13], s[14:15] op_sel_hi:[1,0]
	v_pk_mul_f32 v[20:21], v[4:5], s[14:15] op_sel_hi:[1,0]
	v_exp_f32_e32 v36, v36
	v_exp_f32_e32 v37, v37
	v_pk_add_f32 v[34:35], v[34:35], 1.0 op_sel_hi:[1,0]
	v_pk_add_f32 v[22:23], v[24:25], 1.0 op_sel_hi:[1,0]
	v_exp_f32_e32 v12, v12
	v_exp_f32_e32 v13, v13
	v_pk_add_f32 v[14:15], v[14:15], 1.0 op_sel_hi:[1,0]
	v_exp_f32_e32 v20, v20
	v_exp_f32_e32 v21, v21
	v_rcp_f32_e32 v34, v34
	v_rcp_f32_e32 v35, v35
	v_rcp_f32_e32 v22, v22
	v_rcp_f32_e32 v23, v23
	v_rcp_f32_e32 v14, v14
	v_rcp_f32_e32 v15, v15
	v_pk_add_f32 v[36:37], v[36:37], 1.0 op_sel_hi:[1,0]
	v_pk_add_f32 v[12:13], v[12:13], 1.0 op_sel_hi:[1,0]
	v_pk_mul_f32 v[2:3], v[2:3], v[6:7]
	v_pk_add_f32 v[6:7], v[20:21], 1.0 op_sel_hi:[1,0]
	v_rcp_f32_e32 v36, v36
	v_rcp_f32_e32 v37, v37
	v_pk_mul_f32 v[26:27], v[34:35], v[26:27]
	v_mov_b32_e32 v18, 0
	v_pk_mul_f32 v[10:11], v[22:23], v[10:11]
	v_rcp_f32_e32 v12, v12
	v_rcp_f32_e32 v13, v13
	v_pk_mul_f32 v[2:3], v[14:15], v[2:3]
	v_rcp_f32_e32 v6, v6
	v_rcp_f32_e32 v7, v7
	v_mov_b32_e32 v20, 0
	v_mov_b32_e32 v21, 0
	v_cvt_pk_fp8_f32 v18, v26, v27
	v_cvt_pk_fp8_f32 v20, v10, v11
	v_cvt_pk_fp8_f32 v21, v2, v3
	v_pk_mul_f32 v[2:3], v[4:5], v[8:9]
	v_pk_mul_f32 v[28:29], v[36:37], v[28:29]
	v_pk_mul_f32 v[12:13], v[12:13], v[16:17]
	v_pk_mul_f32 v[2:3], v[6:7], v[2:3]
	v_cvt_pk_fp8_f32 v18, v28, v29 op_sel:[0,0,1]
	v_cvt_pk_fp8_f32 v20, v12, v13 op_sel:[0,0,1]
	v_cvt_pk_fp8_f32 v21, v2, v3 op_sel:[0,0,1]
	v_add_u32_e32 v2, 0x6e000, v102
	s_andn2_b64 vcc, exec, s[2:3]
	v_permlane16_swap_b32_e32 v18, v20
	v_permlane16_swap_b32_e32 v19, v21
	s_mov_b64 s[2:3], -1
	buffer_store_dwordx4 v[18:21], v2, s[4:7], 0 offen
	s_cbranch_vccnz .LBB0_615
	s_andn2_b64 vcc, exec, s[0:1]
	s_cbranch_vccnz .LBB0_614
	s_barrier
	s_branch .LBB0_614
